# attention key loop VALU trim: running -m and all-ones fragments kept in spare VGPRs, row-max trees as v_max3 chains without NaN-canonicalising self-max, plus counted lgkmcnt waits
# speedup vs baseline: 1.0230x; 1.0156x over previous
.LBB0_1320:
	v_readfirstlane_b32 s67, v107
	s_ashr_i32 s61, s67, 6
	s_lshl_b32 s66, s61, 4
	s_and_b32 s70, s66, 48
	v_or_b32_e32 v129, s70, v109
	v_mul_u32_u24_e32 v0, s49, v129
	s_ashr_i32 s23, s67, 8
	v_lshlrev_b32_e32 v0, 1, v0
	v_lshl_add_u64 v[2:3], s[30:31], 0, v[0:1]
	s_lshl_b32 s30, s23, 6
	s_ashr_i32 s31, s30, 31
	v_mul_lo_u32 v8, s49, v120
	v_lshl_add_u64 v[2:3], s[30:31], 1, v[2:3]
	s_lshl_b32 s31, s61, 10
	s_waitcnt vmcnt(0)
	v_mul_lo_u32 v10, s0, v122
	v_mov_b32_e32 v113, v1
	v_add_lshl_u32 v0, v8, v121, 1
	s_add_i32 s76, s2, s31
	v_lshl_add_u64 v[6:7], v[2:3], 0, v[112:113]
	v_add_lshl_u32 v8, v123, v10, 1
	v_lshl_add_u64 v[10:11], s[34:35], 0, v[0:1]
	s_mov_b32 m0, s76
	v_mul_lo_u32 v9, s0, v120
	global_load_dwordx4 v[2:5], v[6:7], off
	global_load_dwordx4 v[14:17], v[6:7], off offset:64
	s_barrier
	s_add_i32 s0, s76, 0xc000
	global_load_lds_dwordx4 v0, s[34:35]
	v_lshl_add_u64 v[10:11], v[10:11], 0, s[44:45]
	s_add_i32 m0, s76, 0x2000
	v_add_lshl_u32 v6, v9, v121, 1
	global_load_lds_dwordx4 v[10:11], off
	s_mov_b32 m0, s0
	s_add_i32 s0, s59, s31
	global_load_lds_dwordx4 v6, s[36:37]
	s_add_i32 m0, s76, 0xe000
	s_lshl_b32 s74, s49, 7
	global_load_lds_dwordx4 v8, s[36:37]
	s_add_i32 m0, s76, 0x4000
	s_add_u32 s50, s34, s74
	s_addc_u32 s51, s35, 0
	v_mov_b32_e32 v7, v1
	s_waitcnt vmcnt(0)
	v_lshl_add_u64 v[18:19], s[50:51], 0, v[0:1]
	v_lshl_add_u64 v[10:11], s[36:37], 0, v[6:7]
	v_mov_b32_e32 v9, v1
	global_load_lds_dwordx4 v0, s[50:51]
	v_lshl_add_u64 v[18:19], v[18:19], 0, s[44:45]
	s_add_i32 m0, s76, 0x6000
	v_lshl_add_u64 v[12:13], s[36:37], 0, v[8:9]
	global_load_lds_dwordx4 v[18:19], off
	v_lshl_add_u64 v[18:19], v[10:11], 0, s[44:45]
	s_mov_b32 m0, s0
	s_mov_b32 s77, 1
	global_load_lds_dwordx4 v[18:19], off
	v_lshl_add_u64 v[18:19], v[12:13], 0, s[44:45]
	s_add_i32 m0, s0, 0x2000
	s_add_i32 s0, s60, s31
	global_load_lds_dwordx4 v[18:19], off
	s_add_i32 m0, s76, 0x8000
	s_add_u32 s50, s50, s74
	s_addc_u32 s51, s51, 0
	v_lshl_add_u64 v[18:19], s[50:51], 0, v[0:1]
	global_load_lds_dwordx4 v0, s[50:51]
	v_lshl_add_u64 v[18:19], v[18:19], 0, s[44:45]
	s_add_i32 m0, s76, 0xa000
	s_mov_b64 s[50:51], 0x100
	global_load_lds_dwordx4 v[18:19], off
	v_lshl_add_u64 v[10:11], v[10:11], 0, s[50:51]
	s_mov_b32 m0, s0
	s_nop 0
	global_load_lds_dwordx4 v[10:11], off
	v_lshl_add_u64 v[10:11], v[12:13], 0, s[50:51]
	s_add_i32 m0, s0, 0x2000
	s_nop 0
	global_load_lds_dwordx4 v[10:11], off
	v_lshlrev_b32_e32 v10, 16, v2
	v_and_b32_e32 v11, 0xffff0000, v2
	s_mov_b32 s0, 0x3e38aa3b
	v_lshlrev_b32_e32 v2, 16, v3
	v_and_b32_e32 v3, 0xffff0000, v3
	v_pk_mul_f32 v[10:11], v[10:11], s[0:1] op_sel_hi:[1,0]
	v_pk_mul_f32 v[2:3], v[2:3], s[0:1] op_sel_hi:[1,0]
	v_cvt_pk_bf16_f32 v10, v10, v11
	v_cvt_pk_bf16_f32 v11, v2, v3
	v_lshlrev_b32_e32 v2, 16, v4
	v_and_b32_e32 v3, 0xffff0000, v4
	v_pk_mul_f32 v[2:3], v[2:3], s[0:1] op_sel_hi:[1,0]
	s_lshl_b32 s50, s23, 13
	v_cvt_pk_bf16_f32 v12, v2, v3
	v_lshlrev_b32_e32 v2, 16, v5
	v_and_b32_e32 v3, 0xffff0000, v5
	v_pk_mul_f32 v[2:3], v[2:3], s[0:1] op_sel_hi:[1,0]
	s_waitcnt vmcnt(8)
	s_barrier
	v_cvt_pk_bf16_f32 v13, v2, v3
	v_lshlrev_b32_e32 v2, 16, v14
	v_and_b32_e32 v3, 0xffff0000, v14
	v_pk_mul_f32 v[2:3], v[2:3], s[0:1] op_sel_hi:[1,0]
	v_add_u32_e32 v34, s50, v124
	v_cvt_pk_bf16_f32 v18, v2, v3
	v_lshlrev_b32_e32 v2, 16, v15
	v_and_b32_e32 v3, 0xffff0000, v15
	v_pk_mul_f32 v[14:15], v[2:3], s[0:1] op_sel_hi:[1,0]
	ds_read_b128 v[2:5], v34
	ds_read_b128 v[22:25], v34 offset:1024
	v_cvt_pk_bf16_f32 v19, v14, v15
	v_lshlrev_b32_e32 v14, 16, v16
	v_and_b32_e32 v15, 0xffff0000, v16
	v_pk_mul_f32 v[14:15], v[14:15], s[0:1] op_sel_hi:[1,0]
	v_lshlrev_b32_e32 v26, 16, v17
	v_cvt_pk_bf16_f32 v20, v14, v15
	v_and_b32_e32 v27, 0xffff0000, v17
	s_waitcnt lgkmcnt(0)
	v_mfma_f32_16x16x32_bf16 v[2:5], v[2:5], v[10:13], 0
	ds_read_b128 v[14:17], v34 offset:2048
	v_pk_mul_f32 v[26:27], v[26:27], s[0:1] op_sel_hi:[1,0]
	ds_read_b128 v[30:33], v34 offset:6144
	v_cvt_pk_bf16_f32 v21, v26, v27
	ds_read_b128 v[26:29], v34 offset:4096
	s_waitcnt lgkmcnt(0)
	v_mfma_f32_16x16x32_bf16 v[30:33], v[30:33], v[10:13], 0
	s_add_i32 s0, s71, -2
	s_mulk_i32 s49, 0x180
	s_add_u32 s34, s34, s49
	v_mfma_f32_16x16x32_bf16 v[22:25], v[22:25], v[18:21], v[2:5]
	s_addc_u32 s35, s35, 0
	v_lshl_add_u64 v[114:115], s[34:35], 0, v[0:1]
	s_add_u32 s34, s36, 0x180
	ds_read_b128 v[2:5], v34 offset:3072
	v_mfma_f32_16x16x32_bf16 v[14:17], v[14:17], v[10:13], 0
	s_mov_b32 s88, s75
	s_mov_b32 s89, s75
	s_addc_u32 s35, s37, 0
	s_waitcnt lgkmcnt(0)
	v_mfma_f32_16x16x32_bf16 v[14:17], v[2:5], v[18:21], v[14:17]
	ds_read_b128 v[2:5], v34 offset:5120
	ds_read_b128 v[34:37], v34 offset:7168
	s_mov_b32 s90, s75
	v_mfma_f32_16x16x32_bf16 v[26:29], v[26:29], v[10:13], 0
	s_mov_b32 s91, s75
	v_lshl_add_u64 v[118:119], s[34:35], 0, v[6:7]
	v_mov_b32_e32 v6, 0
	s_waitcnt lgkmcnt(0)
	v_mfma_f32_16x16x32_bf16 v[26:29], v[2:5], v[18:21], v[26:29]
	v_mov_b64_e32 v[2:3], s[88:89]
	v_mov_b64_e32 v[4:5], s[90:91]
	v_lshl_add_u64 v[116:117], s[34:35], 0, v[8:9]
	v_mfma_f32_16x16x32_bf16 v[30:33], v[34:37], v[18:21], v[30:33]
	v_max_f32_e32 v34, v25, v25
	v_max_f32_e32 v35, v24, v24
	v_max_f32_e32 v34, v35, v34
	v_max_f32_e32 v35, v17, v17
	v_max_f32_e32 v36, v16, v16
	v_max_f32_e32 v35, v36, v35
	v_max_f32_e32 v36, v27, v27
	v_max_f32_e32 v37, v26, v26
	v_max_f32_e32 v36, v37, v36
	v_max_f32_e32 v37, v29, v29
	v_max_f32_e32 v38, v28, v28
	v_max_f32_e32 v37, v38, v37
	v_max_f32_e32 v38, v33, v33
	v_max_f32_e32 v39, v32, v32
	v_max_f32_e32 v38, v39, v38
	v_max3_f32 v38, v30, v31, v38
	v_max3_f32 v34, v22, v23, v34
	v_max3_f32 v35, v14, v15, v35
	v_max3_f32 v36, v36, v37, v38
	v_max3_f32 v34, v34, v35, v36
	v_mov_b32_e32 v35, v34
	s_nop 1
	v_permlane16_swap_b32_e32 v34, v35
	v_max_f32_e32 v35, v35, v35
	v_max_f32_e32 v34, v34, v34
	v_max_f32_e32 v34, v34, v35
	v_mov_b32_e32 v35, v34
	s_nop 1
	v_permlane32_swap_b32_e32 v34, v35
	v_max_f32_e32 v35, v35, v35
	v_max_f32_e32 v34, v34, v34
	v_max_f32_e32 v113, v34, v35
	v_sub_f32_e32 v74, v22, v113
	v_sub_f32_e32 v22, v26, v113
	v_sub_f32_e32 v26, v30, v113
	v_mov_b32_e32 v30, 0
	v_sub_f32_e32 v77, v25, v113
	v_sub_f32_e32 v76, v24, v113
	v_sub_f32_e32 v75, v23, v113
	v_sub_f32_e32 v73, v17, v113
	v_sub_f32_e32 v72, v16, v113
	v_sub_f32_e32 v71, v15, v113
	v_sub_f32_e32 v70, v14, v113
	v_sub_f32_e32 v25, v29, v113
	v_sub_f32_e32 v24, v28, v113
	v_sub_f32_e32 v23, v27, v113
	v_sub_f32_e32 v29, v33, v113
	v_sub_f32_e32 v28, v32, v113
	v_sub_f32_e32 v27, v31, v113
	v_add_u32_e32 v130, s50, v127
	s_mov_b32 s36, 0
	s_mov_b32 s37, 3
	s_mov_b32 s49, 0
	s_mov_b32 s72, 0
	s_mov_b32 s50, 0
	v_mov_b32_e32 v7, v6
	v_mov_b32_e32 v8, v6
	v_mov_b32_e32 v9, v6
	v_mov_b32_e32 v14, v6
	v_mov_b32_e32 v15, v6
	v_mov_b32_e32 v16, v6
	v_mov_b32_e32 v17, v6
	v_mov_b32_e32 v31, v30
	v_mov_b32_e32 v32, v30
	v_mov_b32_e32 v33, v30
	v_mov_b32_e32 v50, v30
	v_mov_b32_e32 v51, v30
	v_mov_b32_e32 v52, v30
	v_mov_b32_e32 v53, v30
	v_mov_b32_e32 v42, v30
	v_mov_b32_e32 v43, v30
	v_mov_b32_e32 v44, v30
	v_mov_b32_e32 v45, v30
	v_mov_b32_e32 v34, v30
	v_mov_b32_e32 v35, v30
	v_mov_b32_e32 v36, v30
	v_mov_b32_e32 v37, v30
	v_mov_b32_e32 v58, v30
	v_mov_b32_e32 v59, v30
	v_mov_b32_e32 v60, v30
	v_mov_b32_e32 v61, v30
	v_mov_b32_e32 v54, v30
	v_mov_b32_e32 v55, v30
	v_mov_b32_e32 v56, v30
	v_mov_b32_e32 v57, v30
	v_mov_b32_e32 v46, v30
	v_mov_b32_e32 v47, v30
	v_mov_b32_e32 v48, v30
	v_mov_b32_e32 v49, v30
	v_mov_b32_e32 v38, v30
	v_mov_b32_e32 v39, v30
	v_mov_b32_e32 v40, v30
	v_mov_b32_e32 v41, v30
	v_xor_b32_e32 v150, 0x80000000, v113
	v_mov_b32_e32 v154, s48
	v_mov_b32_e32 v151, v150
	v_mov_b32_e32 v155, v154
	v_mov_b32_e32 v152, v150
	v_mov_b32_e32 v156, v154
	v_mov_b32_e32 v153, v150
	v_mov_b32_e32 v157, v154
	s_mov_b64 s[88:89], s[86:87]
	s_cmp_ge_u32 s50, s0
	s_mov_b64 s[34:35], -1
	s_cbranch_scc0 .LBB0_1322

.LBB0_1326:
	s_mul_hi_u32 s34, s77, 0xaaaaaaab
	s_lshr_b32 s34, s34, 1
	s_mul_i32 s34, s34, 0xc000
	v_subrev_u32_e32 v0, s34, v130
	s_add_i32 s34, s2, s36
	v_add_u32_e32 v0, s34, v0
	ds_read_b128 v[66:69], v0
	ds_read_b128 v[82:85], v0 offset:4096
	ds_read_b128 v[94:97], v0 offset:6144
	ds_read_b128 v[98:101], v0 offset:1024
	ds_read_b128 v[86:89], v0 offset:2048
	ds_read_b128 v[132:135], v0 offset:3072
	s_lshl_b32 s34, s49, 14
	v_add_u32_e32 v131, s34, v124
	s_waitcnt lgkmcnt(5)
	v_mfma_f32_16x16x32_bf16 v[66:69], v[66:69], v[10:13], v[150:153]
	ds_read_b128 v[78:81], v0 offset:5120
	s_waitcnt lgkmcnt(2)
	v_mfma_f32_16x16x32_bf16 v[136:139], v[86:89], v[10:13], v[150:153]
	v_max3_f32 v102, v74, v75, v76
	v_max3_f32 v102, v102, v77, v70
	v_max3_f32 v102, v102, v71, v72
	v_max_f32_e32 v102, v102, v73
	ds_read_b128 v[86:89], v0 offset:7168
	v_mfma_f32_16x16x32_bf16 v[90:93], v[82:85], v[10:13], v[150:153]
	v_mfma_f32_16x16x32_bf16 v[94:97], v[94:97], v[10:13], v[150:153]
	ds_read_b128 v[82:85], v131 offset:49152
	v_max3_f32 v0, v22, v23, v24
	v_max3_f32 v0, v0, v25, v26
	v_max3_f32 v0, v0, v27, v28
	v_max3_f32 v0, v0, v29, v102
	ds_read_b128 v[102:105], v131 offset:51200
	v_mfma_f32_16x16x32_bf16 v[62:65], v[98:101], v[18:21], v[66:69]
	s_waitcnt lgkmcnt(4)
	v_mfma_f32_16x16x32_bf16 v[66:69], v[132:135], v[18:21], v[136:139]
	v_mov_b32_e32 v132, v0
	s_nop 1
	v_permlane16_swap_b32_e32 v0, v132
	v_max_f32_e32 v0, v0, v132
	v_mov_b32_e32 v132, v0
	s_nop 1
	v_permlane32_swap_b32_e32 v0, v132
	ds_read_b128 v[98:101], v131 offset:53248
	v_max_f32_e32 v0, v0, v132
	s_mov_b32 s34, 0x41000000
	v_cmp_lt_f32_e32 vcc, s34, v0
	s_cmp_lg_u64 vcc, 0
	s_cselect_b64 s[34:35], -1, 0
	s_cbranch_vccz .LBB0_1328
	v_cndmask_b32_e32 v132, 0, v0, vcc
	v_exp_f32_e64 v0, -v132
	v_sub_f32_e32 v74, v74, v132
	v_sub_f32_e32 v75, v75, v132
	v_sub_f32_e32 v76, v76, v132
	v_sub_f32_e32 v77, v77, v132
	v_sub_f32_e32 v70, v70, v132
	v_sub_f32_e32 v71, v71, v132
	v_sub_f32_e32 v72, v72, v132
	v_sub_f32_e32 v73, v73, v132
	v_sub_f32_e32 v22, v22, v132
	v_sub_f32_e32 v23, v23, v132
	v_sub_f32_e32 v24, v24, v132
	v_sub_f32_e32 v25, v25, v132
	v_sub_f32_e32 v26, v26, v132
	v_sub_f32_e32 v27, v27, v132
	v_sub_f32_e32 v28, v28, v132
	v_sub_f32_e32 v29, v29, v132
	v_add_f32_e32 v113, v113, v132
	v_xor_b32_e32 v150, 0x80000000, v113
	v_mov_b32_e32 v151, v150
	v_mov_b32_e32 v152, v150
	v_mov_b32_e32 v153, v150
	s_branch .LBB0_1329

.LBB0_1329:
	v_mov_b32_e32 v133, v22
	v_mov_b32_e32 v138, v23
	v_mov_b32_e32 v139, v24
	v_mov_b32_e32 v140, v25
	v_mov_b32_e32 v141, v26
	v_mov_b32_e32 v142, v27
	v_mov_b32_e32 v143, v28
	v_mov_b32_e32 v144, v29
	ds_read_b128 v[134:137], v131 offset:55296
	s_waitcnt lgkmcnt(5)
	v_mfma_f32_16x16x32_bf16 v[22:25], v[78:81], v[18:21], v[90:93]
	ds_read_b128 v[78:81], v131 offset:57344
	s_waitcnt lgkmcnt(5)
	v_mfma_f32_16x16x32_bf16 v[26:29], v[86:89], v[18:21], v[94:97]
	ds_read_b128 v[86:89], v131 offset:59392
	s_waitcnt lgkmcnt(5)
	v_mfma_f32_16x16x32_bf16 v[30:33], v[82:85], v[14:17], v[30:33]
	v_exp_f32_e32 v145, v74
	v_exp_f32_e32 v146, v75
	v_exp_f32_e32 v147, v76
	v_exp_f32_e32 v148, v77
	ds_read_b128 v[74:77], v131 offset:61440
	s_waitcnt lgkmcnt(5)
	v_mfma_f32_16x16x32_bf16 v[50:53], v[102:105], v[14:17], v[50:53]
	ds_read_b128 v[82:85], v131 offset:63488
	s_waitcnt lgkmcnt(5)
	v_mfma_f32_16x16x32_bf16 v[42:45], v[98:101], v[14:17], v[42:45]
	ds_read_b128 v[90:93], v131 offset:50176
	s_waitcnt lgkmcnt(5)
	v_mfma_f32_16x16x32_bf16 v[34:37], v[134:137], v[14:17], v[34:37]
	v_exp_f32_e32 v98, v70
	v_exp_f32_e32 v99, v71
	v_exp_f32_e32 v100, v72
	v_exp_f32_e32 v101, v73
	ds_read_b128 v[70:73], v131 offset:52224
	s_waitcnt lgkmcnt(5)
	v_mfma_f32_16x16x32_bf16 v[58:61], v[78:81], v[14:17], v[58:61]
	ds_read_b128 v[78:81], v131 offset:54272
	s_waitcnt lgkmcnt(5)
	v_mfma_f32_16x16x32_bf16 v[54:57], v[86:89], v[14:17], v[54:57]
	ds_read_b128 v[86:89], v131 offset:56320
	s_waitcnt lgkmcnt(5)
	v_mfma_f32_16x16x32_bf16 v[46:49], v[74:77], v[14:17], v[46:49]
	v_exp_f32_e32 v102, v133
	v_exp_f32_e32 v103, v138
	v_exp_f32_e32 v104, v139
	v_exp_f32_e32 v105, v140
	ds_read_b128 v[74:77], v131 offset:58368
	s_waitcnt lgkmcnt(5)
	v_mfma_f32_16x16x32_bf16 v[38:41], v[82:85], v[14:17], v[38:41]
	v_mfma_f32_16x16x32_bf16 v[2:5], v[154:157], v[14:17], v[2:5]
	ds_read_b128 v[94:97], v131 offset:60416
	s_waitcnt lgkmcnt(5)
	v_mfma_f32_16x16x32_bf16 v[30:33], v[90:93], v[6:9], v[30:33]
	v_exp_f32_e32 v133, v141
	v_exp_f32_e32 v134, v142
	v_exp_f32_e32 v135, v143
	v_exp_f32_e32 v136, v144
	ds_read_b128 v[90:93], v131 offset:62464
	s_waitcnt lgkmcnt(5)
	v_mfma_f32_16x16x32_bf16 v[50:53], v[70:73], v[6:9], v[50:53]
	ds_read_b128 v[70:73], v131 offset:64512
	s_waitcnt lgkmcnt(5)
	v_mfma_f32_16x16x32_bf16 v[42:45], v[78:81], v[6:9], v[42:45]
	s_waitcnt lgkmcnt(4)
	v_mfma_f32_16x16x32_bf16 v[34:37], v[86:89], v[6:9], v[34:37]
	v_cvt_pk_bf16_f32 v14, v145, v146
	v_cvt_pk_bf16_f32 v15, v147, v148
	v_cvt_pk_bf16_f32 v16, v98, v99
	v_cvt_pk_bf16_f32 v17, v100, v101
	v_cvt_pk_bf16_f32 v78, v102, v103
	v_cvt_pk_bf16_f32 v79, v104, v105
	v_cvt_pk_bf16_f32 v80, v133, v134
	v_cvt_pk_bf16_f32 v81, v135, v136
	s_waitcnt lgkmcnt(3)
	v_mfma_f32_16x16x32_bf16 v[58:61], v[74:77], v[6:9], v[58:61]
	s_waitcnt lgkmcnt(2)
	v_mfma_f32_16x16x32_bf16 v[54:57], v[94:97], v[6:9], v[54:57]
	s_waitcnt lgkmcnt(1)
	v_mfma_f32_16x16x32_bf16 v[46:49], v[90:93], v[6:9], v[46:49]
	s_waitcnt lgkmcnt(0)
	v_mfma_f32_16x16x32_bf16 v[38:41], v[70:73], v[6:9], v[38:41]
	v_mfma_f32_16x16x32_bf16 v[2:5], v[154:157], v[6:9], v[2:5]
	v_mov_b64_e32 v[6:7], v[78:79]
	v_mov_b64_e32 v[8:9], v[80:81]
	s_andn2_b64 vcc, exec, s[34:35]
	s_cbranch_vccnz .LBB0_1331
	v_sub_f32_e32 v65, v65, v132
	v_sub_f32_e32 v64, v64, v132
	v_sub_f32_e32 v63, v63, v132
	v_sub_f32_e32 v62, v62, v132
	v_sub_f32_e32 v69, v69, v132
	v_sub_f32_e32 v68, v68, v132
	v_sub_f32_e32 v67, v67, v132
	v_sub_f32_e32 v66, v66, v132
	v_sub_f32_e32 v25, v25, v132
	v_sub_f32_e32 v24, v24, v132
	v_sub_f32_e32 v23, v23, v132
	v_sub_f32_e32 v22, v22, v132
	v_sub_f32_e32 v29, v29, v132
	v_sub_f32_e32 v28, v28, v132
	v_sub_f32_e32 v27, v27, v132
	v_sub_f32_e32 v26, v26, v132
	v_pk_mul_f32 v[40:41], v[0:1], v[40:41] op_sel_hi:[0,1]
	v_pk_mul_f32 v[48:49], v[0:1], v[48:49] op_sel_hi:[0,1]
	v_pk_mul_f32 v[56:57], v[0:1], v[56:57] op_sel_hi:[0,1]
	v_pk_mul_f32 v[60:61], v[0:1], v[60:61] op_sel_hi:[0,1]
	v_pk_mul_f32 v[36:37], v[0:1], v[36:37] op_sel_hi:[0,1]
	v_pk_mul_f32 v[44:45], v[0:1], v[44:45] op_sel_hi:[0,1]
	v_pk_mul_f32 v[52:53], v[0:1], v[52:53] op_sel_hi:[0,1]
	v_pk_mul_f32 v[32:33], v[0:1], v[32:33] op_sel_hi:[0,1]
	v_pk_mul_f32 v[38:39], v[0:1], v[38:39] op_sel_hi:[0,1]
	v_pk_mul_f32 v[46:47], v[0:1], v[46:47] op_sel_hi:[0,1]
	v_pk_mul_f32 v[54:55], v[0:1], v[54:55] op_sel_hi:[0,1]
	v_pk_mul_f32 v[58:59], v[0:1], v[58:59] op_sel_hi:[0,1]
	v_pk_mul_f32 v[34:35], v[0:1], v[34:35] op_sel_hi:[0,1]
	v_pk_mul_f32 v[42:43], v[0:1], v[42:43] op_sel_hi:[0,1]
	v_pk_mul_f32 v[50:51], v[0:1], v[50:51] op_sel_hi:[0,1]
	v_pk_mul_f32 v[30:31], v[0:1], v[30:31] op_sel_hi:[0,1]
	v_pk_mul_f32 v[4:5], v[0:1], v[4:5] op_sel_hi:[0,1]
	v_pk_mul_f32 v[2:3], v[0:1], v[2:3] op_sel_hi:[0,1]
